# SWIGLU epilogue stores in SGPR-base + 32-bit offset form
# speedup vs baseline: 1.0008x; 1.0008x over previous
; DI unsigned pk2(float lo, float hi) { const f32x2v v = {lo, hi}; const bf16x2v b = __builtin_convertvector(v, bf16x2v); return __builtin_bit_cast(unsigned, b); }
; DI float siluf_(float x) { return x * sigmoidf_(x); }
; DI float rs_of(float ss, float inv_n) { return __builtin_amdgcn_rsqf(ss * inv_n + EPS); }
; DI float sum16_fq(const float* p, int fq) { const f32x4 a = *(const f32x4*)(p + 4 * fq); float s = (a[0] + a[1]) + (a[2] + a[3]); s += __shfl_xor(s, 16); s += __shfl_xor(s, 32); return s; }
; DI void epilogue(int kind, int l, const f32x4 (&acc)[2][2][4][2], const Unit& u, int wr, int wc, int fr, int fq) {
;     ...
;     if (E.mode == EM_SWIGLU) {
; #pragma unroll
;         for (int ai = 0; ai < 2; ++ai)
; #pragma unroll
;             for (int m = 0; m < 4; ++m) { const int row = row0 + ai * HALF + m * 16; const float rs = rs_of(sum16_fq(E.ss_in + (size_t)row * 16, fq), 1.f / 1024.f);
; #pragma unroll
;                 for (int bj = 0; bj < 2; ++bj) { const f32x4 g = acc[ai][bj][m][0] * rs, up = acc[ai][bj][m][1] * rs;
;                     u32x2 w; w.x = pk2(siluf_(g[0]) * up[0], siluf_(g[1]) * up[1]); w.y = pk2(siluf_(g[2]) * up[2], siluf_(g[3]) * up[3]);
;                     *(u32x2*)(E.o0 + (size_t)row * FF + ((col0 + bj * HALF) >> 1)) = w; } }
.LBB0_812:
	v_lshlrev_b32_e32 v24, 2, v166
	s_waitcnt lgkmcnt(0)
	v_lshl_add_u64 v[250:251], s[88:89], 0, v[24:25]
	v_ashrrev_i32_e32 v173, 31, v172
	v_lshlrev_b64 v[130:131], 6, v[172:173]
	v_lshl_add_u64 v[250:251], v[250:251], 0, v[130:131]
	v_mov_b32_e32 v252, 0x2000
	v_mov_b32_e32 v253, 0
	v_lshl_add_u64 v[252:253], v[250:251], 0, v[252:253]
	global_load_dwordx4 v[216:219], v[250:251], off
	global_load_dwordx4 v[220:223], v[250:251], off offset:1024
	global_load_dwordx4 v[224:227], v[250:251], off offset:2048
	global_load_dwordx4 v[228:231], v[250:251], off offset:3072
	global_load_dwordx4 v[232:235], v[252:253], off
	global_load_dwordx4 v[236:239], v[252:253], off offset:1024
	global_load_dwordx4 v[240:243], v[252:253], off offset:2048
	global_load_dwordx4 v[244:247], v[252:253], off offset:3072
	v_xor_b32_e32 v248, 16, v187
	v_xor_b32_e32 v249, 32, v187
	v_lshlrev_b32_e32 v248, 2, v248
	v_lshlrev_b32_e32 v249, 2, v249
	s_movk_i32 s6, 0x1600
	v_mul_lo_u32 v150, v172, s6
	v_and_b32_e32 v24, 16, v187
	v_mul_u32_u24_e32 v24, 0x78, v24
	v_lshrrev_b32_e32 v24, 4, v24
	v_add3_u32 v150, v150, v174, v24
	s_waitcnt vmcnt(0)
	v_add_f32_e32 v216, v217, v216
	v_add_f32_e32 v220, v221, v220
	v_add_f32_e32 v224, v225, v224
	v_add_f32_e32 v228, v229, v228
	v_add_f32_e32 v232, v233, v232
	v_add_f32_e32 v236, v237, v236
	v_add_f32_e32 v240, v241, v240
	v_add_f32_e32 v244, v245, v244
	v_add_f32_e32 v218, v218, v219
	v_add_f32_e32 v222, v222, v223
	v_add_f32_e32 v226, v226, v227
	v_add_f32_e32 v230, v230, v231
	v_add_f32_e32 v234, v234, v235
	v_add_f32_e32 v238, v238, v239
	v_add_f32_e32 v242, v242, v243
	v_add_f32_e32 v246, v246, v247
	v_add_f32_e32 v216, v216, v218
	v_add_f32_e32 v220, v220, v222
	v_add_f32_e32 v224, v224, v226
	v_add_f32_e32 v228, v228, v230
	v_add_f32_e32 v232, v232, v234
	v_add_f32_e32 v236, v236, v238
	v_add_f32_e32 v240, v240, v242
	v_add_f32_e32 v244, v244, v246
	ds_bpermute_b32 v217, v248, v216
	ds_bpermute_b32 v221, v248, v220
	ds_bpermute_b32 v225, v248, v224
	ds_bpermute_b32 v229, v248, v228
	ds_bpermute_b32 v233, v248, v232
	ds_bpermute_b32 v237, v248, v236
	ds_bpermute_b32 v241, v248, v240
	ds_bpermute_b32 v245, v248, v244
	s_waitcnt lgkmcnt(0)
	v_add_f32_e32 v216, v216, v217
	v_add_f32_e32 v220, v220, v221
	v_add_f32_e32 v224, v224, v225
	v_add_f32_e32 v228, v228, v229
	v_add_f32_e32 v232, v232, v233
	v_add_f32_e32 v236, v236, v237
	v_add_f32_e32 v240, v240, v241
	v_add_f32_e32 v244, v244, v245
	ds_bpermute_b32 v217, v249, v216
	ds_bpermute_b32 v221, v249, v220
	ds_bpermute_b32 v225, v249, v224
	ds_bpermute_b32 v229, v249, v228
	ds_bpermute_b32 v233, v249, v232
	ds_bpermute_b32 v237, v249, v236
	ds_bpermute_b32 v241, v249, v240
	ds_bpermute_b32 v245, v249, v244
	s_waitcnt lgkmcnt(0)
	v_add_f32_e32 v216, v216, v217
	v_add_f32_e32 v220, v220, v221
	v_add_f32_e32 v224, v224, v225
	v_add_f32_e32 v228, v228, v229
	v_add_f32_e32 v232, v232, v233
	v_add_f32_e32 v236, v236, v237
	v_add_f32_e32 v240, v240, v241
	v_add_f32_e32 v244, v244, v245
	v_fmamk_f32 v216, v216, 0x3a800000, v185
	v_fmamk_f32 v220, v220, 0x3a800000, v185
	v_fmamk_f32 v224, v224, 0x3a800000, v185
	v_fmamk_f32 v228, v228, 0x3a800000, v185
	v_fmamk_f32 v232, v232, 0x3a800000, v185
	v_fmamk_f32 v236, v236, 0x3a800000, v185
	v_fmamk_f32 v240, v240, 0x3a800000, v185
	v_fmamk_f32 v244, v244, 0x3a800000, v185
	v_rsq_f32_e32 v216, v216
	v_rsq_f32_e32 v220, v220
	v_rsq_f32_e32 v224, v224
	v_rsq_f32_e32 v228, v228
	v_rsq_f32_e32 v232, v232
	v_rsq_f32_e32 v236, v236
	v_rsq_f32_e32 v240, v240
	v_rsq_f32_e32 v244, v244
	v_mul_f32_e32 v217, 0xbfb8aa3b, v216
	v_mul_f32_e32 v221, 0xbfb8aa3b, v220
	v_mul_f32_e32 v225, 0xbfb8aa3b, v224
	v_mul_f32_e32 v229, 0xbfb8aa3b, v228
	v_mul_f32_e32 v233, 0xbfb8aa3b, v232
	v_mul_f32_e32 v237, 0xbfb8aa3b, v236
	v_mul_f32_e32 v241, 0xbfb8aa3b, v240
	v_mul_f32_e32 v245, 0xbfb8aa3b, v244
	v_mul_f32_e32 v218, v216, v216
	v_mul_f32_e32 v222, v220, v220
	v_mul_f32_e32 v226, v224, v224
	v_mul_f32_e32 v230, v228, v228
	v_mul_f32_e32 v234, v232, v232
	v_mul_f32_e32 v238, v236, v236
	v_mul_f32_e32 v242, v240, v240
	v_mul_f32_e32 v246, v244, v244
	v_mul_f32_e32 v130, v126, v217
	v_mul_f32_e32 v131, v127, v217
	v_mul_f32_e32 v132, v128, v217
	v_mul_f32_e32 v133, v129, v217
	v_exp_f32_e32 v130, v130
	v_exp_f32_e32 v131, v131
	v_exp_f32_e32 v132, v132
	v_exp_f32_e32 v133, v133
	v_pk_mul_f32 v[134:135], v[126:127], v[122:123]
	v_pk_mul_f32 v[136:137], v[128:129], v[124:125]
	v_add_f32_e32 v130, 1.0, v130
	v_add_f32_e32 v131, 1.0, v131
	v_add_f32_e32 v132, 1.0, v132
	v_add_f32_e32 v133, 1.0, v133
	v_rcp_f32_e32 v130, v130
	v_rcp_f32_e32 v131, v131
	v_rcp_f32_e32 v132, v132
	v_rcp_f32_e32 v133, v133
	v_pk_mul_f32 v[130:131], v[130:131], v[218:219] op_sel_hi:[1,0]
	v_pk_mul_f32 v[132:133], v[132:133], v[218:219] op_sel_hi:[1,0]
	v_pk_mul_f32 v[134:135], v[134:135], v[130:131]
	v_pk_mul_f32 v[136:137], v[136:137], v[132:133]
	v_cvt_pk_bf16_f32 v138, v134, v135
	v_cvt_pk_bf16_f32 v139, v136, v137
	v_mul_f32_e32 v130, v118, v217
	v_mul_f32_e32 v131, v119, v217
	v_mul_f32_e32 v132, v120, v217
	v_mul_f32_e32 v133, v121, v217
	v_exp_f32_e32 v130, v130
	v_exp_f32_e32 v131, v131
	v_exp_f32_e32 v132, v132
	v_exp_f32_e32 v133, v133
	v_pk_mul_f32 v[134:135], v[118:119], v[114:115]
	v_pk_mul_f32 v[136:137], v[120:121], v[116:117]
	v_add_f32_e32 v130, 1.0, v130
	v_add_f32_e32 v131, 1.0, v131
	v_add_f32_e32 v132, 1.0, v132
	v_add_f32_e32 v133, 1.0, v133
	v_rcp_f32_e32 v130, v130
	v_rcp_f32_e32 v131, v131
	v_rcp_f32_e32 v132, v132
	v_rcp_f32_e32 v133, v133
	v_pk_mul_f32 v[130:131], v[130:131], v[218:219] op_sel_hi:[1,0]
	v_pk_mul_f32 v[132:133], v[132:133], v[218:219] op_sel_hi:[1,0]
; DI unsigned pk2(float lo, float hi) { const f32x2v v = {lo, hi}; const bf16x2v b = __builtin_convertvector(v, bf16x2v); return __builtin_bit_cast(unsigned, b); }
; DI float siluf_(float x) { return x * sigmoidf_(x); }
; DI float rs_of(float ss, float inv_n) { return __builtin_amdgcn_rsqf(ss * inv_n + EPS); }
; DI float sum16_fq(const float* p, int fq) { const f32x4 a = *(const f32x4*)(p + 4 * fq); float s = (a[0] + a[1]) + (a[2] + a[3]); s += __shfl_xor(s, 16); s += __shfl_xor(s, 32); return s; }
; DI void epilogue(int kind, int l, const f32x4 (&acc)[2][2][4][2], const Unit& u, int wr, int wc, int fr, int fq) {
;     ...
;             for (int m = 0; m < 4; ++m) { const int row = row0 + ai * HALF + m * 16; const float rs = rs_of(sum16_fq(E.ss_in + (size_t)row * 16, fq), 1.f / 1024.f);
; #pragma unroll
;                 for (int bj = 0; bj < 2; ++bj) { const f32x4 g = acc[ai][bj][m][0] * rs, up = acc[ai][bj][m][1] * rs;
;                     u32x2 w; w.x = pk2(siluf_(g[0]) * up[0], siluf_(g[1]) * up[1]); w.y = pk2(siluf_(g[2]) * up[2], siluf_(g[3]) * up[3]);
;                     *(u32x2*)(E.o0 + (size_t)row * FF + ((col0 + bj * HALF) >> 1)) = w; } }
	v_pk_mul_f32 v[134:135], v[134:135], v[130:131]
	v_pk_mul_f32 v[136:137], v[136:137], v[132:133]
	v_cvt_pk_bf16_f32 v140, v134, v135
	v_cvt_pk_bf16_f32 v141, v136, v137
	s_nop 1
	v_permlane16_swap_b32_e32 v138, v140
	v_permlane16_swap_b32_e32 v139, v141
	global_store_dwordx4 v150, v[138:141], s[78:79]
	v_add_u32_e32 v150, 0x16000, v150
	v_mul_f32_e32 v130, v110, v221
	v_mul_f32_e32 v131, v111, v221
	v_mul_f32_e32 v132, v112, v221
	v_mul_f32_e32 v133, v113, v221
	v_exp_f32_e32 v130, v130
	v_exp_f32_e32 v131, v131
	v_exp_f32_e32 v132, v132
	v_exp_f32_e32 v133, v133
	v_pk_mul_f32 v[134:135], v[110:111], v[106:107]
	v_pk_mul_f32 v[136:137], v[112:113], v[108:109]
	v_add_f32_e32 v130, 1.0, v130
	v_add_f32_e32 v131, 1.0, v131
	v_add_f32_e32 v132, 1.0, v132
	v_add_f32_e32 v133, 1.0, v133
	v_rcp_f32_e32 v130, v130
	v_rcp_f32_e32 v131, v131
	v_rcp_f32_e32 v132, v132
	v_rcp_f32_e32 v133, v133
	v_pk_mul_f32 v[130:131], v[130:131], v[222:223] op_sel_hi:[1,0]
	v_pk_mul_f32 v[132:133], v[132:133], v[222:223] op_sel_hi:[1,0]
	v_pk_mul_f32 v[134:135], v[134:135], v[130:131]
	v_pk_mul_f32 v[136:137], v[136:137], v[132:133]
	v_cvt_pk_bf16_f32 v142, v134, v135
	v_cvt_pk_bf16_f32 v143, v136, v137
	v_mul_f32_e32 v130, v102, v221
	v_mul_f32_e32 v131, v103, v221
	v_mul_f32_e32 v132, v104, v221
	v_mul_f32_e32 v133, v105, v221
	v_exp_f32_e32 v130, v130
	v_exp_f32_e32 v131, v131
	v_exp_f32_e32 v132, v132
	v_exp_f32_e32 v133, v133
	v_pk_mul_f32 v[134:135], v[102:103], v[98:99]
	v_pk_mul_f32 v[136:137], v[104:105], v[100:101]
	v_add_f32_e32 v130, 1.0, v130
	v_add_f32_e32 v131, 1.0, v131
	v_add_f32_e32 v132, 1.0, v132
	v_add_f32_e32 v133, 1.0, v133
	v_rcp_f32_e32 v130, v130
	v_rcp_f32_e32 v131, v131
	v_rcp_f32_e32 v132, v132
	v_rcp_f32_e32 v133, v133
	v_pk_mul_f32 v[130:131], v[130:131], v[222:223] op_sel_hi:[1,0]
	v_pk_mul_f32 v[132:133], v[132:133], v[222:223] op_sel_hi:[1,0]
	v_pk_mul_f32 v[134:135], v[134:135], v[130:131]
	v_pk_mul_f32 v[136:137], v[136:137], v[132:133]
	v_cvt_pk_bf16_f32 v144, v134, v135
	v_cvt_pk_bf16_f32 v145, v136, v137
	s_nop 1
	v_permlane16_swap_b32_e32 v142, v144
	v_permlane16_swap_b32_e32 v143, v145
	global_store_dwordx4 v150, v[142:145], s[78:79]
	v_add_u32_e32 v150, 0x16000, v150
	v_mul_f32_e32 v130, v94, v225
	v_mul_f32_e32 v131, v95, v225
	v_mul_f32_e32 v132, v96, v225
	v_mul_f32_e32 v133, v97, v225
	v_exp_f32_e32 v130, v130
	v_exp_f32_e32 v131, v131
	v_exp_f32_e32 v132, v132
	v_exp_f32_e32 v133, v133
	v_pk_mul_f32 v[134:135], v[94:95], v[90:91]
	v_pk_mul_f32 v[136:137], v[96:97], v[92:93]
	v_add_f32_e32 v130, 1.0, v130
	v_add_f32_e32 v131, 1.0, v131
	v_add_f32_e32 v132, 1.0, v132
	v_add_f32_e32 v133, 1.0, v133
	v_rcp_f32_e32 v130, v130
	v_rcp_f32_e32 v131, v131
	v_rcp_f32_e32 v132, v132
	v_rcp_f32_e32 v133, v133
	v_pk_mul_f32 v[130:131], v[130:131], v[226:227] op_sel_hi:[1,0]
	v_pk_mul_f32 v[132:133], v[132:133], v[226:227] op_sel_hi:[1,0]
	v_pk_mul_f32 v[134:135], v[134:135], v[130:131]
	v_pk_mul_f32 v[136:137], v[136:137], v[132:133]
	v_cvt_pk_bf16_f32 v138, v134, v135
	v_cvt_pk_bf16_f32 v139, v136, v137
	v_mul_f32_e32 v130, v86, v225
	v_mul_f32_e32 v131, v87, v225
	v_mul_f32_e32 v132, v88, v225
	v_mul_f32_e32 v133, v89, v225
	v_exp_f32_e32 v130, v130
	v_exp_f32_e32 v131, v131
	v_exp_f32_e32 v132, v132
	v_exp_f32_e32 v133, v133
	v_pk_mul_f32 v[134:135], v[86:87], v[82:83]
	v_pk_mul_f32 v[136:137], v[88:89], v[84:85]
	v_add_f32_e32 v130, 1.0, v130
	v_add_f32_e32 v131, 1.0, v131
	v_add_f32_e32 v132, 1.0, v132
	v_add_f32_e32 v133, 1.0, v133
	v_rcp_f32_e32 v130, v130
	v_rcp_f32_e32 v131, v131
	v_rcp_f32_e32 v132, v132
	v_rcp_f32_e32 v133, v133
	v_pk_mul_f32 v[130:131], v[130:131], v[226:227] op_sel_hi:[1,0]
	v_pk_mul_f32 v[132:133], v[132:133], v[226:227] op_sel_hi:[1,0]
	v_pk_mul_f32 v[134:135], v[134:135], v[130:131]
	v_pk_mul_f32 v[136:137], v[136:137], v[132:133]
	v_cvt_pk_bf16_f32 v140, v134, v135
	v_cvt_pk_bf16_f32 v141, v136, v137
	s_nop 1
	v_permlane16_swap_b32_e32 v138, v140
	v_permlane16_swap_b32_e32 v139, v141
	global_store_dwordx4 v150, v[138:141], s[78:79]
	v_add_u32_e32 v150, 0x16000, v150
	v_mul_f32_e32 v130, v78, v229
	v_mul_f32_e32 v131, v79, v229
	v_mul_f32_e32 v132, v80, v229
	v_mul_f32_e32 v133, v81, v229
	v_exp_f32_e32 v130, v130
	v_exp_f32_e32 v131, v131
	v_exp_f32_e32 v132, v132
	v_exp_f32_e32 v133, v133
	v_pk_mul_f32 v[134:135], v[78:79], v[74:75]
	v_pk_mul_f32 v[136:137], v[80:81], v[76:77]
	v_add_f32_e32 v130, 1.0, v130
	v_add_f32_e32 v131, 1.0, v131
	v_add_f32_e32 v132, 1.0, v132
	v_add_f32_e32 v133, 1.0, v133
	v_rcp_f32_e32 v130, v130
	v_rcp_f32_e32 v131, v131
	v_rcp_f32_e32 v132, v132
	v_rcp_f32_e32 v133, v133
	v_pk_mul_f32 v[130:131], v[130:131], v[230:231] op_sel_hi:[1,0]
	v_pk_mul_f32 v[132:133], v[132:133], v[230:231] op_sel_hi:[1,0]
	v_pk_mul_f32 v[134:135], v[134:135], v[130:131]
	v_pk_mul_f32 v[136:137], v[136:137], v[132:133]
	v_cvt_pk_bf16_f32 v142, v134, v135
	v_cvt_pk_bf16_f32 v143, v136, v137
	v_mul_f32_e32 v130, v70, v229
	v_mul_f32_e32 v131, v71, v229
	v_mul_f32_e32 v132, v72, v229
	v_mul_f32_e32 v133, v73, v229
	v_exp_f32_e32 v130, v130
	v_exp_f32_e32 v131, v131
	v_exp_f32_e32 v132, v132
	v_exp_f32_e32 v133, v133
	v_pk_mul_f32 v[134:135], v[70:71], v[66:67]
	v_pk_mul_f32 v[136:137], v[72:73], v[68:69]
	v_add_f32_e32 v130, 1.0, v130
	v_add_f32_e32 v131, 1.0, v131
	v_add_f32_e32 v132, 1.0, v132
	v_add_f32_e32 v133, 1.0, v133
	v_rcp_f32_e32 v130, v130
	v_rcp_f32_e32 v131, v131
	v_rcp_f32_e32 v132, v132
	v_rcp_f32_e32 v133, v133
	v_pk_mul_f32 v[130:131], v[130:131], v[230:231] op_sel_hi:[1,0]
	v_pk_mul_f32 v[132:133], v[132:133], v[230:231] op_sel_hi:[1,0]
	v_pk_mul_f32 v[134:135], v[134:135], v[130:131]
; DI unsigned pk2(float lo, float hi) { const f32x2v v = {lo, hi}; const bf16x2v b = __builtin_convertvector(v, bf16x2v); return __builtin_bit_cast(unsigned, b); }
; DI float siluf_(float x) { return x * sigmoidf_(x); }
; DI float rs_of(float ss, float inv_n) { return __builtin_amdgcn_rsqf(ss * inv_n + EPS); }
; DI float sum16_fq(const float* p, int fq) { const f32x4 a = *(const f32x4*)(p + 4 * fq); float s = (a[0] + a[1]) + (a[2] + a[3]); s += __shfl_xor(s, 16); s += __shfl_xor(s, 32); return s; }
; DI void epilogue(int kind, int l, const f32x4 (&acc)[2][2][4][2], const Unit& u, int wr, int wc, int fr, int fq) {
;     ...
;             for (int m = 0; m < 4; ++m) { const int row = row0 + ai * HALF + m * 16; const float rs = rs_of(sum16_fq(E.ss_in + (size_t)row * 16, fq), 1.f / 1024.f);
; #pragma unroll
;                 for (int bj = 0; bj < 2; ++bj) { const f32x4 g = acc[ai][bj][m][0] * rs, up = acc[ai][bj][m][1] * rs;
;                     u32x2 w; w.x = pk2(siluf_(g[0]) * up[0], siluf_(g[1]) * up[1]); w.y = pk2(siluf_(g[2]) * up[2], siluf_(g[3]) * up[3]);
;                     *(u32x2*)(E.o0 + (size_t)row * FF + ((col0 + bj * HALF) >> 1)) = w; } }
	v_pk_mul_f32 v[136:137], v[136:137], v[132:133]
	v_cvt_pk_bf16_f32 v144, v134, v135
	v_cvt_pk_bf16_f32 v145, v136, v137
	s_nop 1
	v_permlane16_swap_b32_e32 v142, v144
	v_permlane16_swap_b32_e32 v143, v145
	global_store_dwordx4 v150, v[142:145], s[78:79]
	v_add_u32_e32 v150, 0x6e000, v150
	v_mul_f32_e32 v130, v62, v233
	v_mul_f32_e32 v131, v63, v233
	v_mul_f32_e32 v132, v64, v233
	v_mul_f32_e32 v133, v65, v233
	v_exp_f32_e32 v130, v130
	v_exp_f32_e32 v131, v131
	v_exp_f32_e32 v132, v132
	v_exp_f32_e32 v133, v133
	v_pk_mul_f32 v[134:135], v[62:63], v[58:59]
	v_pk_mul_f32 v[136:137], v[64:65], v[60:61]
	v_add_f32_e32 v130, 1.0, v130
	v_add_f32_e32 v131, 1.0, v131
	v_add_f32_e32 v132, 1.0, v132
	v_add_f32_e32 v133, 1.0, v133
	v_rcp_f32_e32 v130, v130
	v_rcp_f32_e32 v131, v131
	v_rcp_f32_e32 v132, v132
	v_rcp_f32_e32 v133, v133
	v_pk_mul_f32 v[130:131], v[130:131], v[234:235] op_sel_hi:[1,0]
	v_pk_mul_f32 v[132:133], v[132:133], v[234:235] op_sel_hi:[1,0]
	v_pk_mul_f32 v[134:135], v[134:135], v[130:131]
	v_pk_mul_f32 v[136:137], v[136:137], v[132:133]
	v_cvt_pk_bf16_f32 v138, v134, v135
	v_cvt_pk_bf16_f32 v139, v136, v137
	v_mul_f32_e32 v130, v54, v233
	v_mul_f32_e32 v131, v55, v233
	v_mul_f32_e32 v132, v56, v233
	v_mul_f32_e32 v133, v57, v233
	v_exp_f32_e32 v130, v130
	v_exp_f32_e32 v131, v131
	v_exp_f32_e32 v132, v132
	v_exp_f32_e32 v133, v133
	v_pk_mul_f32 v[134:135], v[54:55], v[50:51]
	v_pk_mul_f32 v[136:137], v[56:57], v[52:53]
	v_add_f32_e32 v130, 1.0, v130
	v_add_f32_e32 v131, 1.0, v131
	v_add_f32_e32 v132, 1.0, v132
	v_add_f32_e32 v133, 1.0, v133
	v_rcp_f32_e32 v130, v130
	v_rcp_f32_e32 v131, v131
	v_rcp_f32_e32 v132, v132
	v_rcp_f32_e32 v133, v133
	v_pk_mul_f32 v[130:131], v[130:131], v[234:235] op_sel_hi:[1,0]
	v_pk_mul_f32 v[132:133], v[132:133], v[234:235] op_sel_hi:[1,0]
	v_pk_mul_f32 v[134:135], v[134:135], v[130:131]
	v_pk_mul_f32 v[136:137], v[136:137], v[132:133]
	v_cvt_pk_bf16_f32 v140, v134, v135
	v_cvt_pk_bf16_f32 v141, v136, v137
	s_nop 1
	v_permlane16_swap_b32_e32 v138, v140
	v_permlane16_swap_b32_e32 v139, v141
	global_store_dwordx4 v150, v[138:141], s[78:79]
	v_add_u32_e32 v150, 0x16000, v150
	v_mul_f32_e32 v130, v46, v237
	v_mul_f32_e32 v131, v47, v237
	v_mul_f32_e32 v132, v48, v237
	v_mul_f32_e32 v133, v49, v237
	v_exp_f32_e32 v130, v130
	v_exp_f32_e32 v131, v131
	v_exp_f32_e32 v132, v132
	v_exp_f32_e32 v133, v133
	v_pk_mul_f32 v[134:135], v[46:47], v[42:43]
	v_pk_mul_f32 v[136:137], v[48:49], v[44:45]
	v_add_f32_e32 v130, 1.0, v130
	v_add_f32_e32 v131, 1.0, v131
	v_add_f32_e32 v132, 1.0, v132
	v_add_f32_e32 v133, 1.0, v133
	v_rcp_f32_e32 v130, v130
	v_rcp_f32_e32 v131, v131
	v_rcp_f32_e32 v132, v132
	v_rcp_f32_e32 v133, v133
	v_pk_mul_f32 v[130:131], v[130:131], v[238:239] op_sel_hi:[1,0]
	v_pk_mul_f32 v[132:133], v[132:133], v[238:239] op_sel_hi:[1,0]
	v_pk_mul_f32 v[134:135], v[134:135], v[130:131]
	v_pk_mul_f32 v[136:137], v[136:137], v[132:133]
	v_cvt_pk_bf16_f32 v142, v134, v135
	v_cvt_pk_bf16_f32 v143, v136, v137
	v_mul_f32_e32 v130, v38, v237
	v_mul_f32_e32 v131, v39, v237
	v_mul_f32_e32 v132, v40, v237
	v_mul_f32_e32 v133, v41, v237
	v_exp_f32_e32 v130, v130
	v_exp_f32_e32 v131, v131
	v_exp_f32_e32 v132, v132
	v_exp_f32_e32 v133, v133
	v_pk_mul_f32 v[134:135], v[38:39], v[34:35]
	v_pk_mul_f32 v[136:137], v[40:41], v[36:37]
	v_add_f32_e32 v130, 1.0, v130
	v_add_f32_e32 v131, 1.0, v131
	v_add_f32_e32 v132, 1.0, v132
	v_add_f32_e32 v133, 1.0, v133
	v_rcp_f32_e32 v130, v130
	v_rcp_f32_e32 v131, v131
	v_rcp_f32_e32 v132, v132
	v_rcp_f32_e32 v133, v133
	v_pk_mul_f32 v[130:131], v[130:131], v[238:239] op_sel_hi:[1,0]
	v_pk_mul_f32 v[132:133], v[132:133], v[238:239] op_sel_hi:[1,0]
	v_pk_mul_f32 v[134:135], v[134:135], v[130:131]
	v_pk_mul_f32 v[136:137], v[136:137], v[132:133]
	v_cvt_pk_bf16_f32 v144, v134, v135
	v_cvt_pk_bf16_f32 v145, v136, v137
; DI unsigned pk2(float lo, float hi) { const f32x2v v = {lo, hi}; const bf16x2v b = __builtin_convertvector(v, bf16x2v); return __builtin_bit_cast(unsigned, b); }
; DI float siluf_(float x) { return x * sigmoidf_(x); }
; DI float rs_of(float ss, float inv_n) { return __builtin_amdgcn_rsqf(ss * inv_n + EPS); }
; DI float sum16_fq(const float* p, int fq) { const f32x4 a = *(const f32x4*)(p + 4 * fq); float s = (a[0] + a[1]) + (a[2] + a[3]); s += __shfl_xor(s, 16); s += __shfl_xor(s, 32); return s; }
; DI void epilogue(int kind, int l, const f32x4 (&acc)[2][2][4][2], const Unit& u, int wr, int wc, int fr, int fq) {
;     ...
;             for (int m = 0; m < 4; ++m) { const int row = row0 + ai * HALF + m * 16; const float rs = rs_of(sum16_fq(E.ss_in + (size_t)row * 16, fq), 1.f / 1024.f);
; #pragma unroll
;                 for (int bj = 0; bj < 2; ++bj) { const f32x4 g = acc[ai][bj][m][0] * rs, up = acc[ai][bj][m][1] * rs;
;                     u32x2 w; w.x = pk2(siluf_(g[0]) * up[0], siluf_(g[1]) * up[1]); w.y = pk2(siluf_(g[2]) * up[2], siluf_(g[3]) * up[3]);
;                     *(u32x2*)(E.o0 + (size_t)row * FF + ((col0 + bj * HALF) >> 1)) = w; } }
	s_nop 1
	v_permlane16_swap_b32_e32 v142, v144
	v_permlane16_swap_b32_e32 v143, v145
	global_store_dwordx4 v150, v[142:145], s[78:79]
	v_add_u32_e32 v150, 0x16000, v150
	v_mul_f32_e32 v130, v30, v241
	v_mul_f32_e32 v131, v31, v241
	v_mul_f32_e32 v132, v32, v241
	v_mul_f32_e32 v133, v33, v241
	v_exp_f32_e32 v130, v130
	v_exp_f32_e32 v131, v131
	v_exp_f32_e32 v132, v132
	v_exp_f32_e32 v133, v133
	v_pk_mul_f32 v[134:135], v[30:31], v[26:27]
	v_pk_mul_f32 v[136:137], v[32:33], v[28:29]
	v_add_f32_e32 v130, 1.0, v130
	v_add_f32_e32 v131, 1.0, v131
	v_add_f32_e32 v132, 1.0, v132
	v_add_f32_e32 v133, 1.0, v133
	v_rcp_f32_e32 v130, v130
	v_rcp_f32_e32 v131, v131
	v_rcp_f32_e32 v132, v132
	v_rcp_f32_e32 v133, v133
	v_pk_mul_f32 v[130:131], v[130:131], v[242:243] op_sel_hi:[1,0]
	v_pk_mul_f32 v[132:133], v[132:133], v[242:243] op_sel_hi:[1,0]
	v_pk_mul_f32 v[134:135], v[134:135], v[130:131]
	v_pk_mul_f32 v[136:137], v[136:137], v[132:133]
	v_cvt_pk_bf16_f32 v138, v134, v135
	v_cvt_pk_bf16_f32 v139, v136, v137
	v_mul_f32_e32 v130, v20, v241
	v_mul_f32_e32 v131, v21, v241
	v_mul_f32_e32 v132, v22, v241
	v_mul_f32_e32 v133, v23, v241
	v_exp_f32_e32 v130, v130
	v_exp_f32_e32 v131, v131
	v_exp_f32_e32 v132, v132
	v_exp_f32_e32 v133, v133
	v_pk_mul_f32 v[134:135], v[20:21], v[16:17]
	v_pk_mul_f32 v[136:137], v[22:23], v[18:19]
	v_add_f32_e32 v130, 1.0, v130
	v_add_f32_e32 v131, 1.0, v131
	v_add_f32_e32 v132, 1.0, v132
	v_add_f32_e32 v133, 1.0, v133
	v_rcp_f32_e32 v130, v130
	v_rcp_f32_e32 v131, v131
	v_rcp_f32_e32 v132, v132
	v_rcp_f32_e32 v133, v133
	v_pk_mul_f32 v[130:131], v[130:131], v[242:243] op_sel_hi:[1,0]
	v_pk_mul_f32 v[132:133], v[132:133], v[242:243] op_sel_hi:[1,0]
	v_pk_mul_f32 v[134:135], v[134:135], v[130:131]
	v_pk_mul_f32 v[136:137], v[136:137], v[132:133]
	v_cvt_pk_bf16_f32 v140, v134, v135
	v_cvt_pk_bf16_f32 v141, v136, v137
	s_nop 1
	v_permlane16_swap_b32_e32 v138, v140
	v_permlane16_swap_b32_e32 v139, v141
	global_store_dwordx4 v150, v[138:141], s[78:79]
	v_add_u32_e32 v150, 0x16000, v150
	v_mul_f32_e32 v130, v12, v245
	v_mul_f32_e32 v131, v13, v245
	v_mul_f32_e32 v132, v14, v245
	v_mul_f32_e32 v133, v15, v245
	v_exp_f32_e32 v130, v130
	v_exp_f32_e32 v131, v131
	v_exp_f32_e32 v132, v132
	v_exp_f32_e32 v133, v133
	v_pk_mul_f32 v[134:135], v[12:13], v[8:9]
	v_pk_mul_f32 v[136:137], v[14:15], v[10:11]
	v_add_f32_e32 v130, 1.0, v130
	v_add_f32_e32 v131, 1.0, v131
	v_add_f32_e32 v132, 1.0, v132
	v_add_f32_e32 v133, 1.0, v133
	v_rcp_f32_e32 v130, v130
	v_rcp_f32_e32 v131, v131
	v_rcp_f32_e32 v132, v132
	v_rcp_f32_e32 v133, v133
	v_pk_mul_f32 v[130:131], v[130:131], v[246:247] op_sel_hi:[1,0]
	v_pk_mul_f32 v[132:133], v[132:133], v[246:247] op_sel_hi:[1,0]
	v_pk_mul_f32 v[134:135], v[134:135], v[130:131]
	v_pk_mul_f32 v[136:137], v[136:137], v[132:133]
	v_cvt_pk_bf16_f32 v142, v134, v135
	v_cvt_pk_bf16_f32 v143, v136, v137
	v_mul_f32_e32 v130, v4, v245
	v_mul_f32_e32 v131, v5, v245
	v_mul_f32_e32 v132, v6, v245
	v_mul_f32_e32 v133, v7, v245
	v_exp_f32_e32 v130, v130
	v_exp_f32_e32 v131, v131
	v_exp_f32_e32 v132, v132
	v_exp_f32_e32 v133, v133
	v_pk_mul_f32 v[134:135], v[4:5], v[0:1]
	v_pk_mul_f32 v[136:137], v[6:7], v[2:3]
	v_add_f32_e32 v130, 1.0, v130
	v_add_f32_e32 v131, 1.0, v131
	v_add_f32_e32 v132, 1.0, v132
	v_add_f32_e32 v133, 1.0, v133
	v_rcp_f32_e32 v130, v130
	v_rcp_f32_e32 v131, v131
	v_rcp_f32_e32 v132, v132
	v_rcp_f32_e32 v133, v133
	v_pk_mul_f32 v[130:131], v[130:131], v[246:247] op_sel_hi:[1,0]
	v_pk_mul_f32 v[132:133], v[132:133], v[246:247] op_sel_hi:[1,0]
	v_pk_mul_f32 v[134:135], v[134:135], v[130:131]
	v_pk_mul_f32 v[136:137], v[136:137], v[132:133]
	v_cvt_pk_bf16_f32 v144, v134, v135
	v_cvt_pk_bf16_f32 v145, v136, v137
	s_nop 1
	v_permlane16_swap_b32_e32 v142, v144
	v_permlane16_swap_b32_e32 v143, v145
	global_store_dwordx4 v150, v[142:145], s[78:79]
